# C2a split-K partial loads issued together; A1 first tile loads before Q wait
# baseline (speedup 1.0000x reference)
; DI unsigned cvtpk(float lo, float hi) { f32x2 v = {lo, hi}; bf16x2_t b = __builtin_convertvector(v, bf16x2_t); return __builtin_bit_cast(unsigned, b); }
; __global__ void __launch_bounds__(512) mega_fwd(Params P) {
;     ...
;             const f32x4* part = (const f32x4*)WSP(float, WS_PART);
;             for (int e = bid * 512 + tid; e < 4096 * 64; e += G * 512) {
;                 f32x4 a = part[e] + part[e + (size_t)4096 * 64] + part[e + (size_t)2 * 4096 * 64] + part[e + (size_t)3 * 4096 * 64];
; #pragma unroll
;                 for (int i = 0; i < 4; ++i) { const float x = a[i], y = 0.7978845608028654f * (x + 0.044715f * x * x * x); a[i] = x * __builtin_amdgcn_rcpf(1.f + __expf(-2.f * y)); }
;                 u32x2 w; w.x = cvtpk(a[0], a[1]); w.y = cvtpk(a[2], a[3]);
;                 *(u32x2*)(HID + (size_t)e * 4) = w;
;             }
.LBB0_920:
	v_add_co_u32_e32 v8, vcc, 0xff400000, v6
	v_add_u32_e32 v2, s2, v2
	s_nop 0
	v_addc_co_u32_e32 v9, vcc, -1, v7, vcc
	v_add_co_u32_e32 v12, vcc, 0xff800000, v6
	flat_load_dwordx4 v[8:11], v[8:9]
	s_nop 0
	v_addc_co_u32_e32 v13, vcc, -1, v7, vcc
	flat_load_dwordx4 v[12:15], v[12:13]
	v_add_co_u32_e32 v16, vcc, 0xffc00000, v6
	s_nop 1
	v_addc_co_u32_e32 v17, vcc, -1, v7, vcc
	flat_load_dwordx4 v[16:19], v[16:17]
	flat_load_dwordx4 v[20:23], v[6:7]
	s_mov_b32 s3, 0x3ffff
	v_cmp_lt_i32_e32 vcc, s3, v2
	s_or_b64 s[8:9], vcc, s[8:9]
	v_lshl_add_u64 v[6:7], v[6:7], 0, s[6:7]
	s_waitcnt vmcnt(0) lgkmcnt(0)
	v_pk_add_f32 v[12:13], v[8:9], v[12:13]
	v_pk_add_f32 v[14:15], v[10:11], v[14:15]
	v_pk_add_f32 v[14:15], v[14:15], v[18:19]
	v_pk_add_f32 v[12:13], v[12:13], v[16:17]
	v_mov_b64_e32 v[10:11], v[22:23]
	v_pk_add_f32 v[8:9], v[12:13], v[20:21]
	s_nop 0
	v_mul_f32_e32 v0, 0x3d372713, v8
	v_mul_f32_e32 v0, v8, v0
	v_fma_f32 v0, v8, v0, v8
	v_mul_f32_e32 v0, 0x3f4c422a, v0
	v_mul_f32_e32 v0, -2.0, v0
	v_mul_f32_e32 v0, 0x3fb8aa3b, v0
	v_exp_f32_e32 v0, v0
	v_pk_add_f32 v[10:11], v[14:15], v[10:11]
	v_add_f32_e32 v0, 1.0, v0
	v_rcp_f32_e32 v12, v0
	v_mul_f32_e32 v0, 0x3d372713, v9
	v_mul_f32_e32 v0, v9, v0
	v_fma_f32 v0, v9, v0, v9
	v_mul_f32_e32 v0, 0x3f4c422a, v0
	v_mul_f32_e32 v0, -2.0, v0
	v_mul_f32_e32 v0, 0x3fb8aa3b, v0
	v_exp_f32_e32 v0, v0
	s_nop 0
	v_add_f32_e32 v0, 1.0, v0
	v_rcp_f32_e32 v13, v0
	v_mul_f32_e32 v0, 0x3d372713, v10
	v_mul_f32_e32 v0, v10, v0
	v_fma_f32 v0, v10, v0, v10
	v_mul_f32_e32 v0, 0x3f4c422a, v0
	v_mul_f32_e32 v0, -2.0, v0
	v_mul_f32_e32 v0, 0x3fb8aa3b, v0
	v_exp_f32_e32 v0, v0
	v_pk_mul_f32 v[8:9], v[8:9], v[12:13]
	v_add_f32_e32 v0, 1.0, v0
	v_rcp_f32_e32 v12, v0
	v_mul_f32_e32 v0, 0x3d372713, v11
	v_mul_f32_e32 v0, v11, v0
	v_fma_f32 v0, v11, v0, v11
	v_mul_f32_e32 v0, 0x3f4c422a, v0
	v_mul_f32_e32 v0, -2.0, v0
	v_mul_f32_e32 v0, 0x3fb8aa3b, v0
	v_exp_f32_e32 v0, v0
	v_cvt_pk_bf16_f32 v8, v8, v9
	v_add_f32_e32 v0, 1.0, v0
	v_rcp_f32_e32 v13, v0
	s_nop 0
	v_pk_mul_f32 v[10:11], v[10:11], v[12:13]
	s_nop 0
	v_cvt_pk_bf16_f32 v9, v10, v11
	flat_store_dwordx2 v[4:5], v[8:9]
	v_lshl_add_u64 v[4:5], v[4:5], 0, s[4:5]
	s_andn2_b64 exec, exec, s[8:9]
	s_cbranch_execnz .LBB0_920

; #define FL_LSTORE(buf) do { *(LAS u32x4*)(lds + AT_K + (buf) * KBUF + srow * KP2 + sch * 16) = rk1; \
;         if (DQK == 96 && tid < 256) *(LAS u32x4*)(lds + AT_K + (buf) * KBUF + srow2 * KP2 + 128 + sch2 * 16) = rk2; \
;         *(LAS u32x4*)(lds + AT_V + (buf) * VBUF + srow * VP2 + sch * 16) = rv; } while (0)
; #define GATES WSP(float, WS_GATES)
; #define LSE WSP(float, WS_LSE)
; #define lds fresh_lds(lds0)
; template <int DQK, int MODE> ...
;     ...
;     FL_GLOAD(t0);
;     __syncthreads();
;     FL_LSTORE(0);
;     if (t0 + 1 < t1) FL_GLOAD(t0 + 1);
;     __syncthreads();
; __global__ void __launch_bounds__(512) mega_fwd(Params P) {
;     ...
;                 const int qb = 31 - it / 12, bh = it % 12, b = bh / 6, h = bh % 6, g = h / 3, q0 = qb * 256;
;                 const size_t rb = (size_t)b * SEQ;
;                 const int cmax = (q0 + 224) >> 4, t1 = (cmax >> 6) + 1;
;                 const float gate = GATES[(rb + q0 + 32 * wid + r32) * 32 + h * 3 + 0];
;                 f32x16 tot[2]; tot[0] = (f32x16){}; tot[1] = (f32x16){};
;                 flash_unit<64, MODE_CMP>(lds, wv0, PROJ + (rb + q0) * NPROJ + PC_NQ + 64 * h, NPROJ, KCVC + ((size_t)(b * NCMP) * 2 + g) * 256, 512, nullptr, 0,
;                                          KCVC + ((size_t)2048 + (size_t)(b * NCMP) * 2 + g) * 256 + 64, 512, q0, 0, t1, 0.125f * LOG2E, (u32x4){}, gate, tot,
;                                          LSE + (size_t)(b * 6 + h) * SEQ + q0);
.LBB0_1072:
	s_or_b64 exec, exec, s[4:5]
	v_mov_b32_e32 v0, s16
	s_waitcnt lgkmcnt(0)
	s_barrier
	ds_read_b32 v0, v0
	s_movk_i32 s4, 0x17f
	s_waitcnt lgkmcnt(0)
	v_cmp_lt_i32_e32 vcc, s4, v0
	v_readfirstlane_b32 s6, v0
	s_mov_b64 s[4:5], -1
	s_cbranch_vccnz .LBB0_1069
	s_mul_hi_i32 s4, s6, 0xd5555555
	s_lshr_b32 s5, s4, 31
	s_lshr_b32 s4, s4, 1
	s_add_i32 s5, s4, s5
	s_mul_hi_i32 s4, s6, 0x2aaaaaab
	s_lshr_b32 s7, s4, 31
	s_lshr_b32 s4, s4, 1
	s_add_i32 s4, s4, s7
	s_mul_i32 s4, s4, 12
	s_sub_i32 s6, s6, s4
	s_bfe_i32 s4, s6, 0x80000
	s_mul_i32 s4, s4, 43
	s_bfe_u32 s7, s4, 0x1000f
	s_bfe_u32 s4, s4, 0x80008
	s_add_i32 s4, s4, s7
	s_mul_i32 s7, s4, 6
	s_sub_i32 s6, s6, s7
	s_sext_i32_i8 s21, s6
	s_bfe_i32 s6, s6, 0x80000
	s_mulk_i32 s6, 0x56
	s_bfe_u32 s7, s6, 0x1000f
	s_bfe_u32 s6, s6, 0x80008
	s_lshl_b32 s24, s5, 8
	s_bfe_i64 s[12:13], s[4:5], 0x80000
	s_add_i32 s6, s6, s7
	s_add_i32 s28, s24, 0x1f00
	s_lshl_b64 s[12:13], s[12:13], 13
	s_addk_i32 s24, 0x1fe0
	s_add_u32 s12, s12, s28
	s_addc_u32 s13, s13, 0
	s_mul_i32 s22, s21, 3
	s_mul_i32 s5, s13, 0x1400
	s_mul_hi_u32 s7, s12, 0x1400
	s_ashr_i32 s23, s22, 31
	s_add_i32 s7, s7, s5
	s_mul_i32 s5, s12, 0x1400
	v_lshl_add_u64 v[126:127], s[12:13], 0, v[122:123]
	s_add_u32 s5, s14, s5
	v_lshlrev_b64 v[2:3], 7, v[126:127]
	s_addc_u32 s7, s15, s7
	s_lshl_b32 s12, s21, 6
	s_mov_b32 s29, s81
	v_lshl_add_u64 v[2:3], s[8:9], 0, v[2:3]
	s_ashr_i32 s13, s12, 31
	v_lshl_add_u64 v[2:3], s[22:23], 2, v[2:3]
	s_mov_b32 s22, s29
	s_lshl_b64 s[26:27], s[12:13], 1
	v_mov_b32_e32 v0, v1
	flat_load_dword v125, v[2:3]
	s_add_u32 s5, s5, s26
	s_addc_u32 s7, s7, s27
	v_mbcnt_lo_u32_b32 v0, -1, v0
	s_add_u32 s26, s5, 0x3c00340
	v_mbcnt_hi_u32_b32 v3, -1, v0
	s_addc_u32 s27, s7, 0
	v_and_b32_e32 v4, 31, v3
	v_readlane_b32 s5, v254, 6
	v_bfe_u32 v2, v3, 5, 1
	v_mov_b64_e32 v[6:7], s[26:27]
	v_or_b32_e32 v128, s5, v4
	v_mad_i64_i32 v[6:7], s[26:27], v128, s69, v[6:7]
	v_lshlrev_b32_e32 v0, 4, v2
	v_lshl_add_u64 v[6:7], v[6:7], 0, v[0:1]
	flat_load_dwordx4 v[66:69], v[6:7]
	flat_load_dwordx4 v[70:73], v[6:7] offset:32
	flat_load_dwordx4 v[74:77], v[6:7] offset:64
	flat_load_dwordx4 v[78:81], v[6:7] offset:96
	s_sext_i32_i8 s23, s4
	s_mul_i32 s4, s23, 0x1ff
	s_ashr_i32 s5, s4, 31
	s_bfe_i64 s[6:7], s[6:7], 0x80000
	s_lshl_b64 s[4:5], s[4:5], 10
	s_lshl_b64 s[6:7], s[6:7], 9
	s_add_u32 s4, s17, s4
	v_or_b32_e32 v0, s79, v3
	s_addc_u32 s5, s18, s5
	v_lshlrev_b32_e32 v5, 4, v3
	v_ashrrev_i32_e32 v7, 3, v0
	s_add_u32 s4, s4, s6
	v_and_b32_e32 v5, 0x70, v5
	v_lshlrev_b32_e32 v6, 10, v7
	s_addc_u32 s5, s5, s7
	v_or_b32_e32 v0, v6, v5
	s_add_u32 s6, s4, 0x100080
	v_lshl_add_u64 v[8:9], s[4:5], 0, v[0:1]
	s_addc_u32 s7, s5, 0
	v_lshl_add_u64 v[10:11], s[6:7], 0, v[0:1]
	s_movk_i32 s25, 0x90
	v_mul_lo_u32 v0, v7, s25
	s_mov_b64 s[80:81], s[28:29]
	v_add3_u32 v130, s22, v0, v5
	s_cmpk_lt_u32 s24, 0x400
	flat_load_dwordx4 v[82:85], v[8:9]
	flat_load_dwordx4 v[86:89], v[10:11]
	s_waitcnt vmcnt(0) lgkmcnt(0)
	s_waitcnt lgkmcnt(0)
	s_barrier
	s_waitcnt vmcnt(0)
	ds_write_b128 v130, v[82:85]
	ds_write_b128 v130, v[86:89] offset:28672
	s_cbranch_scc1 .LBB0_1075
	v_add3_u32 v0, v6, v5, s66
	v_lshl_add_u64 v[8:9], s[4:5], 0, v[0:1]
	v_lshl_add_u64 v[10:11], s[6:7], 0, v[0:1]
	flat_load_dwordx4 v[82:85], v[8:9]
	flat_load_dwordx4 v[86:89], v[10:11]
